# dilated attention compute: one static s_setprio 1 for waves 4-7 per unit (7.4), reset at the unit epilogue
# baseline (speedup 1.0000x reference)
.Lpfret_L1:
	s_cmp_eq_u32 s15, 0
	s_cselect_b32 s12, 2, 0
	s_max_i32 s12, s30, s12
	s_cmp_gt_i32 s12, s31
	s_cbranch_scc1 .LBB0_1729
	s_cmp_gt_i32 s30, 1
	s_cbranch_scc0 .Lnp_L1
	s_setprio 1
.Lnp_L1:
	s_mul_i32 s13, s12, 0x3000
	s_add_i32 s43, s12, -1
	v_add_u32_e32 v4, s13, v126
	s_lshl_b32 s13, s12, 6
	s_mulk_i32 s12, 0x2400
	s_add_i32 s16, s42, 0xffffff9f
	v_add_u32_e32 v3, 0xffffff80, v120
	s_add_i32 s44, s14, s13
	v_add_u32_e32 v5, s12, v127

.LBB0_1730:
	s_setprio 0
	v_mov_b32_e32 v0, v121
	s_nop 1
	v_permlane32_swap_b32 v121, v0
	s_nop 1
	s_mov_b64 s[12:13], -1
	v_add_f32_e32 v3, v121, v0
	s_and_b64 vcc, exec, s[24:25]
	s_cbranch_vccnz .LBB0_1732
	s_andn2_b64 vcc, exec, s[12:13]
	s_cbranch_vccnz .LBB0_1685
	s_branch .LBB0_1735

.Lpfret_L3:
	s_cmp_eq_u32 s13, 0
	s_cselect_b32 s10, 2, 0
	s_max_i32 s10, s30, s10
	s_cmp_gt_i32 s10, s31
	s_cbranch_scc1 .LBB0_3830
	s_cmp_gt_i32 s30, 1
	s_cbranch_scc0 .Lnp_L3
	s_setprio 1
.Lnp_L3:
	s_mul_i32 s11, s10, 0x3000
	s_add_i32 s43, s10, -1
	v_add_u32_e32 v4, s11, v126
	s_lshl_b32 s11, s10, 6
	s_mulk_i32 s10, 0x2400
	s_add_i32 s14, s42, 0xffffff9f
	v_add_u32_e32 v3, 0xffffff80, v120
	s_add_i32 s44, s12, s11
	v_add_u32_e32 v5, s10, v127

.LBB0_3831:
	s_setprio 0
	v_mov_b32_e32 v0, v121
	s_nop 1
	v_permlane32_swap_b32 v121, v0
	s_nop 1
	s_mov_b64 s[10:11], -1
	v_add_f32_e32 v3, v121, v0
	s_and_b64 vcc, exec, s[22:23]
	s_cbranch_vccnz .LBB0_3833
	s_andn2_b64 vcc, exec, s[10:11]
	s_cbranch_vccnz .LBB0_3786
	s_branch .LBB0_3836
